# census: 16 first-barrier counter loads issued together; attention unit->block map permuted inside each class so every workgroup gets 97-98 stream steps
# speedup vs baseline: 1.0072x; 1.0003x over previous
; __global__ void __launch_bounds__(512, 2) fwd_megakernel(Args args) {
;     ...
;             for (int u = bx; u < 1024; u += G) {
;                 const int r = u >> 8, wq = u & 255, slot = wq >> 3, i = slot & 15, bg = (wq & 7) * 2 + (slot >> 4);
;                 const int pb = r == 0 ? 63 - i : (r == 1 ? 32 + i : (r == 2 ? 31 - i : i));
;                 const bool build = bg != last_bg; last_bg = bg;
;                 attn_unit(bg, pb, build, (const bf16*)(ws + WS_Q), (const bf16*)(ws + WS_KV), (const bf16*)(ws + WS_KCN), (const bf16*)(ws + WS_VCT), (const float*)(ws + WS_GATES), par + PAR_RELB, (bf16*)(ws + WS_A), lds);
.LBB0_233:
	s_bfe_u32 s7, s2, 0x40003
	s_cmpk_gt_u32 s2, 0xff
	s_mov_b64 s[0:1], -1
	s_cbranch_scc0 .LBB0_239
	s_ashr_i32 s10, s2, 8
	s_cmp_lg_u32 s10, 1
	s_cbranch_scc0 .LBB0_236
	s_mov_b32 s0, 0xda2c9ef8
	s_mov_b32 s1, 0x4716b035
	s_lshl_b32 s88, s7, 2
	s_lshr_b64 s[0:1], s[0:1], s88
	s_and_b32 s0, s0, 15
	s_or_b32 s0, s0, 16
	s_cmp_eq_u32 s10, 2
	s_cselect_b32 s88, s0, s7
	s_mov_b64 s[0:1], 0
.LBB0_236:
	s_andn2_b64 vcc, exec, s[0:1]
	s_cbranch_vccnz .LBB0_238
	s_mov_b32 s0, 0x93c5fbed
	s_mov_b32 s1, 0x207416a8
	s_lshl_b32 s88, s7, 2
	s_lshr_b64 s[0:1], s[0:1], s88
	s_and_b32 s0, s0, 15
	s_or_b32 s88, s0, 32

; __global__ void __launch_bounds__(512, 2) fwd_megakernel(Args args) {
;     ...
;             for (int u = bx; u < 1024; u += G) {
;                 const int r = u >> 8, wq = u & 255, slot = wq >> 3, i = slot & 15, bg = (wq & 7) * 2 + (slot >> 4);
;                 const int pb = r == 0 ? 63 - i : (r == 1 ? 32 + i : (r == 2 ? 31 - i : i));
;                 const bool build = bg != last_bg; last_bg = bg;
;                 attn_unit(bg, pb, build, (const bf16*)(ws + WS_Q), (const bf16*)(ws + WS_KV), (const bf16*)(ws + WS_KCN), (const bf16*)(ws + WS_VCT), (const float*)(ws + WS_GATES), par + PAR_RELB, (bf16*)(ws + WS_A), lds);
.LBB0_239:
	s_andn2_b64 vcc, exec, s[0:1]
	s_cbranch_vccnz .LBB0_241
	s_mov_b32 s0, 0x2deca68f
	s_mov_b32 s1, 0x10534b97
	s_lshl_b32 s88, s7, 2
	s_lshr_b64 s[0:1], s[0:1], s88
	s_and_b32 s0, s0, 15
	s_or_b32 s88, s0, 48

; __device__ __forceinline__ unsigned xb_ld(unsigned* p)              { return __hip_atomic_load(p, __ATOMIC_RELAXED, __HIP_MEMORY_SCOPE_AGENT); }
; __device__ __forceinline__ void xcd_barrier_complete(unsigned* bar, unsigned x, unsigned& nloc, unsigned& nx) {
;     const unsigned G = gridDim.x * gridDim.y * gridDim.z;
;     unsigned sum, cnt, mine, sp = 0u;
;     for (;;) {
;         sum = 0u; cnt = 0u; mine = 0u;
; #pragma unroll
;         for (unsigned j = 0; j < 16; ++j) { const unsigned c = xb_ld(&bar[XB_XCNT(j)]); sum += c; cnt += (c > 0u) ? 1u : 0u; mine = (j == x) ? c : mine; }
;         if (sum == G) break;
;         __builtin_amdgcn_s_sleep(1);
;         if ((++sp & 255u) == 0u) { if (xb_ld(&bar[XB_TMO])) break; if (sp > XB_SPIN_CAP) { atomicAdd(&bar[XB_TMO], 1u); break; } }
;     }
.LBB0_1629:
	v_readlane_b32 s4, v253, 44
	v_readlane_b32 s5, v253, 45
	global_load_dword v0, v1, s[22:23] sc1
	s_mov_b64 s[6:7], -1
	s_waitcnt lgkmcnt(0)
	s_nop 1
	global_load_dword v2, v1, s[4:5] sc1
	v_readlane_b32 s4, v253, 46
	v_readlane_b32 s5, v253, 47
	s_nop 1
	s_nop 2
	global_load_dword v3, v1, s[4:5] sc1
	v_readlane_b32 s4, v253, 48
	v_readlane_b32 s5, v253, 49
	s_nop 1
	s_nop 2
	global_load_dword v4, v1, s[4:5] sc1
	v_readlane_b32 s4, v253, 50
	v_readlane_b32 s5, v253, 51
	s_nop 1
	s_nop 2
	global_load_dword v5, v1, s[4:5] sc1
	v_readlane_b32 s4, v253, 52
	v_readlane_b32 s5, v253, 53
	s_nop 1
	s_nop 2
	global_load_dword v6, v1, s[4:5] sc1
	v_readlane_b32 s4, v253, 54
	v_readlane_b32 s5, v253, 55
	s_nop 1
	s_nop 2
	global_load_dword v7, v1, s[4:5] sc1
	v_readlane_b32 s4, v253, 56
	v_readlane_b32 s5, v253, 57
	s_nop 1
	s_nop 2
	global_load_dword v8, v1, s[4:5] sc1
	v_readlane_b32 s4, v253, 58
	v_readlane_b32 s5, v253, 59
	s_nop 1
	s_nop 2
	global_load_dword v9, v1, s[4:5] sc1
	v_readlane_b32 s4, v253, 60
	v_readlane_b32 s5, v253, 61
	s_nop 1
	s_nop 2
	global_load_dword v10, v1, s[4:5] sc1
	v_readlane_b32 s4, v253, 62
	v_readlane_b32 s5, v253, 63
	s_nop 1
	s_nop 2
	global_load_dword v11, v1, s[4:5] sc1
	v_readlane_b32 s4, v254, 0
	v_readlane_b32 s5, v254, 1
	s_nop 1
	s_nop 2
	global_load_dword v12, v1, s[4:5] sc1
	v_readlane_b32 s4, v254, 2
	v_readlane_b32 s5, v254, 3
	s_nop 1
	s_nop 2
	global_load_dword v13, v1, s[4:5] sc1
	v_readlane_b32 s4, v254, 4
	v_readlane_b32 s5, v254, 5
	s_nop 1
	s_nop 2
	global_load_dword v14, v1, s[4:5] sc1
	v_readlane_b32 s4, v254, 6
	v_readlane_b32 s5, v254, 7
	s_nop 1
	s_nop 2
	global_load_dword v15, v1, s[4:5] sc1
	v_readlane_b32 s4, v254, 8
	v_readlane_b32 s5, v254, 9
	s_nop 1
	s_nop 2
	global_load_dword v16, v1, s[4:5] sc1
	s_mov_b64 s[4:5], -1
	s_waitcnt vmcnt(0)
	v_add_u32_e32 v17, v2, v0
	v_add_u32_e32 v17, v17, v3
	v_add_u32_e32 v17, v17, v4
	v_add_u32_e32 v17, v17, v5
	v_add_u32_e32 v17, v17, v6
	v_add_u32_e32 v17, v17, v7
	v_add_u32_e32 v17, v17, v8
	v_add_u32_e32 v17, v17, v9
	v_add_u32_e32 v17, v17, v10
	v_add_u32_e32 v17, v17, v11
	v_add_u32_e32 v17, v17, v12
	v_add_u32_e32 v17, v17, v13
	v_add_u32_e32 v17, v17, v14
	v_add_u32_e32 v17, v17, v15
	v_add_u32_e32 v17, v17, v16
	v_cmp_eq_u32_e32 vcc, s29, v17
	s_cbranch_vccnz .LBB0_1628
	s_and_b32 s4, s3, 0xff
	s_cmp_eq_u32 s4, 0
	s_mov_b64 s[4:5], -1
	s_mov_b64 s[10:11], -1
	s_sleep 1
	s_cbranch_scc0 .LBB0_1633
	v_readlane_b32 s4, v253, 42
	v_readlane_b32 s5, v253, 43
	s_nop 4
	global_load_dword v17, v1, s[4:5] sc1
	s_waitcnt vmcnt(0)
	v_cmp_eq_u32_e32 vcc, 0, v17
	s_cbranch_vccnz .LBB0_1635
	s_mov_b64 s[10:11], 0
	s_mov_b64 s[4:5], -1
